# transposes tiles additionally moved into P0 (311 single-job blocks x 6 tiles); P0b now covers tiles below 29814
# baseline (speedup 1.0000x reference)
; #define GSYNC() do { xcd_barrier(xb); if (REP_MASK & 256) xcd_barrier(xb); } while (0)
; #define LAUNDER(v) asm volatile("" : "+s"(v))
; __device__ __forceinline__ int vtid() { int t = threadIdx.x; asm volatile("" : "+v"(t)); return t; }
; __device__ __forceinline__ void p0_transposes(const Params& p, char* smem, int bid, int nb, int jlo, int jhi) {
;   const int tid = vtid();
;   char* ws = p.ws;
;   LAUNDER(ws);
;   float* tileA = (float*)smem;
;   float* tileB = tileA + 64 * 65;
;   float4 c0[4], c1[4], n0[4], n1[4];
;   int j = jlo + bid * 2;
;   if (j < jhi) { tr_load(p, ws, j, tid, c0); tr_load(p, ws, j + 1, tid, c1); }
;   for (; j < jhi; j += 2 * nb) {
; __global__ void __launch_bounds__(256, 2) fwd_megakernel(Params p) {
;     ...
;   for (int job = NJ_TR + bid; job < NJ_P0; job += nb) p0_job(p, smem, job);
;   GSYNC();
.Ltrp0_check:
	v_readlane_b32 s0, v239, 0
	s_cmpk_lt_i32 s0, 201
	s_cbranch_scc1 .LBB0_94
	v_readlane_b32 s100, v236, 62
	v_readlane_b32 s101, v236, 63
	v_writelane_b32 v255, s64, 0
	v_writelane_b32 v255, s65, 1
	v_writelane_b32 v255, s66, 2
	v_writelane_b32 v255, s67, 3
	v_writelane_b32 v255, s68, 4
	v_writelane_b32 v255, s69, 5
	v_writelane_b32 v255, s70, 6
	v_writelane_b32 v255, s71, 7
	v_writelane_b32 v255, s72, 8
	v_writelane_b32 v255, s73, 9
	v_writelane_b32 v255, s74, 10
	v_writelane_b32 v255, s75, 11
	v_writelane_b32 v255, s76, 12
	v_writelane_b32 v255, s77, 13
	v_writelane_b32 v255, s78, 14
	v_writelane_b32 v255, s79, 15
	v_writelane_b32 v255, s80, 16
	v_writelane_b32 v255, s81, 17
	v_writelane_b32 v255, s82, 18
	v_writelane_b32 v255, s83, 19
	v_writelane_b32 v255, s84, 20
	v_writelane_b32 v255, s85, 21
	v_writelane_b32 v255, s86, 22
	v_writelane_b32 v255, s87, 23
	v_writelane_b32 v255, s88, 24
	v_writelane_b32 v255, s89, 25
	v_writelane_b32 v255, s90, 26
	v_writelane_b32 v255, s91, 27
	v_writelane_b32 v255, s92, 28
	v_writelane_b32 v255, s93, 29
	v_writelane_b32 v255, s94, 30
	v_writelane_b32 v255, s95, 31
	v_writelane_b32 v255, s96, 32
	v_writelane_b32 v255, s97, 33
	v_writelane_b32 v255, s98, 34
	v_writelane_b32 v255, s99, 35
	v_writelane_b32 v255, vcc_lo, 36
	v_writelane_b32 v255, vcc_hi, 37
	s_load_dwordx4 s[64:67], s[100:101], 0x40
	s_load_dwordx4 s[68:71], s[100:101], 0xc8
	s_load_dwordx2 s[72:73], s[100:101], 0xd8
	s_load_dwordx2 s[74:75], s[100:101], 0xe8
	v_and_b32_e32 v241, 15, v172
	v_lshrrev_b32_e32 v242, 4, v172
	v_lshlrev_b32_e32 v241, 4, v241
	v_mul_u32_u24_e32 v243, 0x104, v242
	v_add_u32_e32 v243, v243, v241
	v_and_b32_e32 v246, 7, v172
	v_lshrrev_b32_e32 v245, 3, v172
	v_mul_u32_u24_e32 v244, 0x820, v246
	v_lshl_add_u32 v244, v245, 2, v244
	v_lshlrev_b32_e32 v246, 4, v246
	v_readlane_b32 s76, v239, 0
	s_add_u32 s76, s76, 29613
	s_movk_i32 s77, 3
	s_mov_b32 s96, 0
	s_waitcnt lgkmcnt(0)
.Ltrp0_batch:
	s_min_u32 s78, s76, 31679
	s_cmp_ge_u32 s78, 25472
	s_cselect_b32 s79, 1, 0
	s_cselect_b32 s85, 25472, 0
	s_sub_u32 s78, s78, s85
	s_cmp_lt_u32 s78, 640
	s_cbranch_scc0 .Ltr_p0l0_notin
	s_mul_hi_u32 s80, s78, 107374183
	s_mul_i32 s85, s80, 40
	s_sub_u32 s81, s78, s85
	s_movk_i32 s82, 2560
	s_movk_i32 s83, 1024
	s_mov_b32 s84, -1
	s_mul_i32 s85, s79, 10485760
	s_add_u32 s86, s64, s85
	s_addc_u32 s87, s65, 0
	s_mul_i32 s85, s79, 5242880
	s_add_u32 s88, s74, s85
	s_addc_u32 s89, s75, 0
	s_branch .Ltr_p0l0_dec_done

; __device__ __forceinline__ TrJob tr_decode(const Params& p, char* ws, int job) {
;   TrJob t;
;   int l = job / TJ_PER_LAYER, rj = job % TJ_PER_LAYER;
;   if (rj < 640) {
;     t.src = p.w_in + (size_t)l * 1024 * 2560; t.K = 1024; t.N = 2560; t.kt = rj / 40; t.nt = rj % 40;
;     t.dst = (u16*)(ws + OFF_WINT) + (size_t)l * 2560 * 1024; t.mode = 0;
; __device__ __forceinline__ void tr_load(const Params& p, char* ws, int job, int tid, float4 (&r)[4]) {
;   TrJob t = tr_decode(p, ws, job);
;   const int c4 = tid & 15, rr = tid >> 4;
;   const float* s0 = t.src + (size_t)(t.kt * 64 + rr) * t.N + t.nt * 64 + c4 * 4;
; #pragma unroll
;   for (int pp = 0; pp < 4; ++pp) {
;     f32x4 v_ = __builtin_nontemporal_load((const f32x4*)(s0 + (size_t)(16 * pp) * t.N));
;     r[pp] = make_float4(v_[0], v_[1], v_[2], v_[3]);
;   }
; }
.Ltr_p0l0_dec_done:
	s_mul_i32 s85, s80, s82
	s_lshl_b32 s85, s85, 8
	s_lshl_b32 s79, s81, 8
	s_add_u32 s85, s85, s79
	s_add_u32 s90, s86, s85
	s_addc_u32 s91, s87, 0
	s_lshl_b32 s92, s82, 2
	s_lshl_b32 s93, s82, 6
	v_mad_u32_u24 v240, v242, s92, v241
	global_load_dwordx4 v[212:215], v240, s[90:91] nt
	v_add_u32_e32 v211, s93, v240
	global_load_dwordx4 v[216:219], v211, s[90:91] nt
	v_add_u32_e32 v240, s93, v211
	global_load_dwordx4 v[220:223], v240, s[90:91] nt
	v_add_u32_e32 v211, s93, v240
	global_load_dwordx4 v[224:227], v211, s[90:91] nt
	s_add_u32 s76, s76, 311
	s_min_u32 s78, s76, 31679
	s_cmp_ge_u32 s78, 25472
	s_cselect_b32 s79, 1, 0
	s_cselect_b32 s85, 25472, 0
	s_sub_u32 s78, s78, s85
	s_cmp_lt_u32 s78, 640
	s_cbranch_scc0 .Ltr_p0l1_notin
	s_mul_hi_u32 s80, s78, 107374183
	s_mul_i32 s85, s80, 40
	s_sub_u32 s81, s78, s85
	s_movk_i32 s82, 2560
	s_movk_i32 s83, 1024
	s_mov_b32 s84, -1
	s_mul_i32 s85, s79, 10485760
	s_add_u32 s86, s64, s85
	s_addc_u32 s87, s65, 0
	s_mul_i32 s85, s79, 5242880
	s_add_u32 s88, s74, s85
	s_addc_u32 s89, s75, 0
	s_branch .Ltr_p0l1_dec_done

; __device__ __forceinline__ void tr_load(const Params& p, char* ws, int job, int tid, float4 (&r)[4]) {
;   TrJob t = tr_decode(p, ws, job);
;   const int c4 = tid & 15, rr = tid >> 4;
;   const float* s0 = t.src + (size_t)(t.kt * 64 + rr) * t.N + t.nt * 64 + c4 * 4;
; #pragma unroll
;   for (int pp = 0; pp < 4; ++pp) {
;     f32x4 v_ = __builtin_nontemporal_load((const f32x4*)(s0 + (size_t)(16 * pp) * t.N));
;     r[pp] = make_float4(v_[0], v_[1], v_[2], v_[3]);
;   }
; }
; __device__ __forceinline__ void tr_lds_write(float* tile, int tid, const float4 (&r)[4]) {
;   const int c4 = tid & 15, rr = tid >> 4;
; #pragma unroll
;   for (int pp = 0; pp < 4; ++pp) {
;     float* t = &tile[(rr + 16 * pp) * 65 + c4 * 4];
;     t[0] = r[pp].x; t[1] = r[pp].y; t[2] = r[pp].z; t[3] = r[pp].w;
;   }
; }
; __device__ __forceinline__ void tr_store(const Params& p, char* ws, int job, int tid, const float* tile) {
;   TrJob t = tr_decode(p, ws, job);
;   const int kc = tid & 7, nn = tid >> 3;
; #pragma unroll
;   for (int pp = 0; pp < 2; ++pp) {
;     int n = nn + 32 * pp;
;     float v[8];
; #pragma unroll
;     for (int j = 0; j < 8; ++j) v[j] = tile[(kc * 8 + j) * 65 + n];
.Ltr_p0l1_dec_done:
	s_mul_i32 s85, s80, s82
	s_lshl_b32 s85, s85, 8
	s_lshl_b32 s79, s81, 8
	s_add_u32 s85, s85, s79
	s_add_u32 s90, s86, s85
	s_addc_u32 s91, s87, 0
	s_lshl_b32 s92, s82, 2
	s_lshl_b32 s93, s82, 6
	v_mad_u32_u24 v240, v242, s92, v241
	global_load_dwordx4 v[228:231], v240, s[90:91] nt
	v_add_u32_e32 v211, s93, v240
	global_load_dwordx4 v[232:235], v211, s[90:91] nt
	v_add_u32_e32 v240, s93, v211
	global_load_dwordx4 v[186:189], v240, s[90:91] nt
	v_add_u32_e32 v211, s93, v240
	global_load_dwordx4 v[190:193], v211, s[90:91] nt
	s_add_u32 s76, s76, 311
	s_sub_u32 s76, s76, 622
	s_waitcnt vmcnt(0)
	v_add_u32_e32 v247, s96, v243
	ds_write_b32 v247, v212 offset:0
	ds_write_b32 v247, v213 offset:4
	ds_write_b32 v247, v214 offset:8
	ds_write_b32 v247, v215 offset:12
	ds_write_b32 v247, v216 offset:4160
	ds_write_b32 v247, v217 offset:4164
	ds_write_b32 v247, v218 offset:4168
	ds_write_b32 v247, v219 offset:4172
	ds_write_b32 v247, v220 offset:8320
	ds_write_b32 v247, v221 offset:8324
	ds_write_b32 v247, v222 offset:8328
	ds_write_b32 v247, v223 offset:8332
	ds_write_b32 v247, v224 offset:12480
	ds_write_b32 v247, v225 offset:12484
	ds_write_b32 v247, v226 offset:12488
	ds_write_b32 v247, v227 offset:12492
	v_add_u32_e32 v247, s96, v244
	s_waitcnt lgkmcnt(0)
	s_barrier
	ds_read_b32 v212, v247 offset:0
	ds_read_b32 v213, v247 offset:260
	ds_read_b32 v214, v247 offset:520
	ds_read_b32 v215, v247 offset:780
	ds_read_b32 v216, v247 offset:1040
	ds_read_b32 v217, v247 offset:1300
	ds_read_b32 v218, v247 offset:1560
	ds_read_b32 v219, v247 offset:1820
	ds_read_b32 v220, v247 offset:128
	ds_read_b32 v221, v247 offset:388
	ds_read_b32 v222, v247 offset:648
	ds_read_b32 v223, v247 offset:908
	ds_read_b32 v224, v247 offset:1168
	ds_read_b32 v225, v247 offset:1428
	ds_read_b32 v226, v247 offset:1688
	ds_read_b32 v227, v247 offset:1948
	s_min_u32 s78, s76, 31679
	s_cmp_ge_u32 s78, 25472
	s_cselect_b32 s79, 1, 0
	s_cselect_b32 s85, 25472, 0
	s_sub_u32 s78, s78, s85
	s_cmp_lt_u32 s78, 640
	s_cbranch_scc0 .Ltr_p0s0_notin
	s_mul_hi_u32 s80, s78, 107374183
	s_mul_i32 s85, s80, 40
	s_sub_u32 s81, s78, s85
	s_movk_i32 s82, 2560
	s_movk_i32 s83, 1024
	s_mov_b32 s84, -1
	s_mul_i32 s85, s79, 10485760
	s_add_u32 s86, s64, s85
	s_addc_u32 s87, s65, 0
	s_mul_i32 s85, s79, 5242880
	s_add_u32 s88, s74, s85
	s_addc_u32 s89, s75, 0
	s_branch .Ltr_p0s0_dec_done

; __device__ __forceinline__ unsigned pack2(float a, float b) { return (unsigned)f2bf(a) | ((unsigned)f2bf(b) << 16); }
; __device__ __forceinline__ void tr_lds_write(float* tile, int tid, const float4 (&r)[4]) {
;   const int c4 = tid & 15, rr = tid >> 4;
; #pragma unroll
;   for (int pp = 0; pp < 4; ++pp) {
;     float* t = &tile[(rr + 16 * pp) * 65 + c4 * 4];
;     t[0] = r[pp].x; t[1] = r[pp].y; t[2] = r[pp].z; t[3] = r[pp].w;
;   }
; }
; __device__ __forceinline__ void tr_store(const Params& p, char* ws, int job, int tid, const float* tile) {
;   TrJob t = tr_decode(p, ws, job);
;   const int kc = tid & 7, nn = tid >> 3;
; #pragma unroll
;   for (int pp = 0; pp < 2; ++pp) {
;     int n = nn + 32 * pp;
;     float v[8];
; #pragma unroll
;     for (int j = 0; j < 8; ++j) v[j] = tile[(kc * 8 + j) * 65 + n];
;     uint4 o;
;     o.x = pack2(v[0], v[1]); o.y = pack2(v[2], v[3]); o.z = pack2(v[4], v[5]); o.w = pack2(v[6], v[7]);
;     int gn = t.nt * 64 + n;
;     int drow = t.mode == 0 ? gn : gu_row(t.mode - 1, gn);
;     *(uint4*)&t.dst[(size_t)drow * t.K + t.kt * 64 + kc * 8] = o;
;   }
; }
.Ltr_p0s0_dec_done:
	s_lshl_b32 s97, s83, 1
	s_cmp_eq_u32 s84, -1
	s_cselect_b32 s79, 6, 7
	s_cselect_b32 s85, 32, 64
	s_cselect_b32 s78, 0, s84
	s_lshl_b32 s79, s81, s79
	s_add_u32 s79, s79, s78
	s_add_u32 s85, s85, s79
	s_mul_i32 s79, s79, s97
	s_mul_i32 s85, s85, s97
	s_lshl_b32 s78, s80, 7
	s_add_u32 s79, s79, s78
	s_add_u32 s85, s85, s78
	s_add_u32 s94, s88, s79
	s_addc_u32 s95, s89, 0
	s_add_u32 s98, s88, s85
	s_addc_u32 s99, s89, 0
	v_mad_u32_u24 v254, v245, s97, v246
	s_movk_i32 s78, 0x7fff
	s_mov_b32 s79, 0xffff0000
	s_waitcnt lgkmcnt(0)
	v_bfe_u32 v252, v212, 16, 1
	v_bfe_u32 v253, v213, 16, 1
	v_add3_u32 v252, v212, v252, s78
	v_add3_u32 v253, v213, v253, s78
	v_lshrrev_b32_e32 v252, 16, v252
	v_and_or_b32 v248, v253, s79, v252
	v_bfe_u32 v252, v214, 16, 1
	v_bfe_u32 v253, v215, 16, 1
	v_add3_u32 v252, v214, v252, s78
	v_add3_u32 v253, v215, v253, s78
	v_lshrrev_b32_e32 v252, 16, v252
	v_and_or_b32 v249, v253, s79, v252
	v_bfe_u32 v252, v216, 16, 1
	v_bfe_u32 v253, v217, 16, 1
	v_add3_u32 v252, v216, v252, s78
	v_add3_u32 v253, v217, v253, s78
	v_lshrrev_b32_e32 v252, 16, v252
	v_and_or_b32 v250, v253, s79, v252
	v_bfe_u32 v252, v218, 16, 1
	v_bfe_u32 v253, v219, 16, 1
	v_add3_u32 v252, v218, v252, s78
	v_add3_u32 v253, v219, v253, s78
	v_lshrrev_b32_e32 v252, 16, v252
	v_and_or_b32 v251, v253, s79, v252
	global_store_dwordx4 v254, v[248:251], s[94:95]
	s_nop 1
	v_bfe_u32 v252, v220, 16, 1
	v_bfe_u32 v253, v221, 16, 1
	v_add3_u32 v252, v220, v252, s78
	v_add3_u32 v253, v221, v253, s78
	v_lshrrev_b32_e32 v252, 16, v252
	v_and_or_b32 v248, v253, s79, v252
	v_bfe_u32 v252, v222, 16, 1
	v_bfe_u32 v253, v223, 16, 1
	v_add3_u32 v252, v222, v252, s78
	v_add3_u32 v253, v223, v253, s78
	v_lshrrev_b32_e32 v252, 16, v252
	v_and_or_b32 v249, v253, s79, v252
	v_bfe_u32 v252, v224, 16, 1
	v_bfe_u32 v253, v225, 16, 1
	v_add3_u32 v252, v224, v252, s78
	v_add3_u32 v253, v225, v253, s78
	v_lshrrev_b32_e32 v252, 16, v252
	v_and_or_b32 v250, v253, s79, v252
	v_bfe_u32 v252, v226, 16, 1
	v_bfe_u32 v253, v227, 16, 1
	v_add3_u32 v252, v226, v252, s78
	v_add3_u32 v253, v227, v253, s78
	v_lshrrev_b32_e32 v252, 16, v252
	v_and_or_b32 v251, v253, s79, v252
	global_store_dwordx4 v254, v[248:251], s[98:99]
	s_xor_b32 s96, s96, 0x4100
	s_add_u32 s76, s76, 311
	v_add_u32_e32 v247, s96, v243
	ds_write_b32 v247, v228 offset:0
	ds_write_b32 v247, v229 offset:4
	ds_write_b32 v247, v230 offset:8
	ds_write_b32 v247, v231 offset:12
	ds_write_b32 v247, v232 offset:4160
	ds_write_b32 v247, v233 offset:4164
	ds_write_b32 v247, v234 offset:4168
	ds_write_b32 v247, v235 offset:4172
	ds_write_b32 v247, v186 offset:8320
	ds_write_b32 v247, v187 offset:8324
	ds_write_b32 v247, v188 offset:8328
	ds_write_b32 v247, v189 offset:8332
	ds_write_b32 v247, v190 offset:12480
	ds_write_b32 v247, v191 offset:12484
	ds_write_b32 v247, v192 offset:12488
	ds_write_b32 v247, v193 offset:12492
	v_add_u32_e32 v247, s96, v244
	s_waitcnt lgkmcnt(0)
	s_barrier
	ds_read_b32 v228, v247 offset:0
	ds_read_b32 v229, v247 offset:260
	ds_read_b32 v230, v247 offset:520
	ds_read_b32 v231, v247 offset:780
	ds_read_b32 v232, v247 offset:1040
	ds_read_b32 v233, v247 offset:1300
	ds_read_b32 v234, v247 offset:1560
	ds_read_b32 v235, v247 offset:1820
	ds_read_b32 v186, v247 offset:128
	ds_read_b32 v187, v247 offset:388
	ds_read_b32 v188, v247 offset:648
	ds_read_b32 v189, v247 offset:908
	ds_read_b32 v190, v247 offset:1168
	ds_read_b32 v191, v247 offset:1428
	ds_read_b32 v192, v247 offset:1688
	ds_read_b32 v193, v247 offset:1948
	s_min_u32 s78, s76, 31679
	s_cmp_ge_u32 s78, 25472
	s_cselect_b32 s79, 1, 0
	s_cselect_b32 s85, 25472, 0
	s_sub_u32 s78, s78, s85
	s_cmp_lt_u32 s78, 640
	s_cbranch_scc0 .Ltr_p0s1_notin
	s_mul_hi_u32 s80, s78, 107374183
	s_mul_i32 s85, s80, 40
	s_sub_u32 s81, s78, s85
	s_movk_i32 s82, 2560
	s_movk_i32 s83, 1024
	s_mov_b32 s84, -1
	s_mul_i32 s85, s79, 10485760
	s_add_u32 s86, s64, s85
	s_addc_u32 s87, s65, 0
	s_mul_i32 s85, s79, 5242880
	s_add_u32 s88, s74, s85
	s_addc_u32 s89, s75, 0
	s_branch .Ltr_p0s1_dec_done

; #define LAUNDER(v) asm volatile("" : "+s"(v))
; __device__ __forceinline__ int vtid() { int t = threadIdx.x; asm volatile("" : "+v"(t)); return t; }
; __device__ __forceinline__ unsigned pack2(float a, float b) { return (unsigned)f2bf(a) | ((unsigned)f2bf(b) << 16); }
; __device__ __forceinline__ void tr_store(const Params& p, char* ws, int job, int tid, const float* tile) {
;   TrJob t = tr_decode(p, ws, job);
;   const int kc = tid & 7, nn = tid >> 3;
; #pragma unroll
;   for (int pp = 0; pp < 2; ++pp) {
;     int n = nn + 32 * pp;
;     float v[8];
; #pragma unroll
;     for (int j = 0; j < 8; ++j) v[j] = tile[(kc * 8 + j) * 65 + n];
;     uint4 o;
;     o.x = pack2(v[0], v[1]); o.y = pack2(v[2], v[3]); o.z = pack2(v[4], v[5]); o.w = pack2(v[6], v[7]);
;     int gn = t.nt * 64 + n;
;     int drow = t.mode == 0 ? gn : gu_row(t.mode - 1, gn);
;     *(uint4*)&t.dst[(size_t)drow * t.K + t.kt * 64 + kc * 8] = o;
;   }
; }
; __device__ __forceinline__ void p0_transposes(const Params& p, char* smem, int bid, int nb, int jlo, int jhi) {
;   const int tid = vtid();
;   char* ws = p.ws;
;   LAUNDER(ws);
;   float* tileA = (float*)smem;
;   float* tileB = tileA + 64 * 65;
;   float4 c0[4], c1[4], n0[4], n1[4];
;   int j = jlo + bid * 2;
;   if (j < jhi) { tr_load(p, ws, j, tid, c0); tr_load(p, ws, j + 1, tid, c1); }
;   for (; j < jhi; j += 2 * nb) {
;     const int jn = j + 2 * nb;
;     if (jn < jhi) { tr_load(p, ws, jn, tid, n0); tr_load(p, ws, jn + 1, tid, n1); }
;     tr_lds_write(tileA, tid, c0);
;     tr_lds_write(tileB, tid, c1);
;     __syncthreads();
;     tr_store(p, ws, j, tid, tileA);
;     tr_store(p, ws, j + 1, tid, tileB);
;     __syncthreads();
; #pragma unroll
;     for (int q = 0; q < 4; ++q) { c0[q] = n0[q]; c1[q] = n1[q]; }
;   }
.Ltr_p0s1_dec_done:
	s_lshl_b32 s97, s83, 1
	s_cmp_eq_u32 s84, -1
	s_cselect_b32 s79, 6, 7
	s_cselect_b32 s85, 32, 64
	s_cselect_b32 s78, 0, s84
	s_lshl_b32 s79, s81, s79
	s_add_u32 s79, s79, s78
	s_add_u32 s85, s85, s79
	s_mul_i32 s79, s79, s97
	s_mul_i32 s85, s85, s97
	s_lshl_b32 s78, s80, 7
	s_add_u32 s79, s79, s78
	s_add_u32 s85, s85, s78
	s_add_u32 s94, s88, s79
	s_addc_u32 s95, s89, 0
	s_add_u32 s98, s88, s85
	s_addc_u32 s99, s89, 0
	v_mad_u32_u24 v254, v245, s97, v246
	s_movk_i32 s78, 0x7fff
	s_mov_b32 s79, 0xffff0000
	s_waitcnt lgkmcnt(0)
	v_bfe_u32 v252, v228, 16, 1
	v_bfe_u32 v253, v229, 16, 1
	v_add3_u32 v252, v228, v252, s78
	v_add3_u32 v253, v229, v253, s78
	v_lshrrev_b32_e32 v252, 16, v252
	v_and_or_b32 v248, v253, s79, v252
	v_bfe_u32 v252, v230, 16, 1
	v_bfe_u32 v253, v231, 16, 1
	v_add3_u32 v252, v230, v252, s78
	v_add3_u32 v253, v231, v253, s78
	v_lshrrev_b32_e32 v252, 16, v252
	v_and_or_b32 v249, v253, s79, v252
	v_bfe_u32 v252, v232, 16, 1
	v_bfe_u32 v253, v233, 16, 1
	v_add3_u32 v252, v232, v252, s78
	v_add3_u32 v253, v233, v253, s78
	v_lshrrev_b32_e32 v252, 16, v252
	v_and_or_b32 v250, v253, s79, v252
	v_bfe_u32 v252, v234, 16, 1
	v_bfe_u32 v253, v235, 16, 1
	v_add3_u32 v252, v234, v252, s78
	v_add3_u32 v253, v235, v253, s78
	v_lshrrev_b32_e32 v252, 16, v252
	v_and_or_b32 v251, v253, s79, v252
	global_store_dwordx4 v254, v[248:251], s[94:95]
	s_nop 1
	v_bfe_u32 v252, v186, 16, 1
	v_bfe_u32 v253, v187, 16, 1
	v_add3_u32 v252, v186, v252, s78
	v_add3_u32 v253, v187, v253, s78
	v_lshrrev_b32_e32 v252, 16, v252
	v_and_or_b32 v248, v253, s79, v252
	v_bfe_u32 v252, v188, 16, 1
	v_bfe_u32 v253, v189, 16, 1
	v_add3_u32 v252, v188, v252, s78
	v_add3_u32 v253, v189, v253, s78
	v_lshrrev_b32_e32 v252, 16, v252
	v_and_or_b32 v249, v253, s79, v252
	v_bfe_u32 v252, v190, 16, 1
	v_bfe_u32 v253, v191, 16, 1
	v_add3_u32 v252, v190, v252, s78
	v_add3_u32 v253, v191, v253, s78
	v_lshrrev_b32_e32 v252, 16, v252
	v_and_or_b32 v250, v253, s79, v252
	v_bfe_u32 v252, v192, 16, 1
	v_bfe_u32 v253, v193, 16, 1
	v_add3_u32 v252, v192, v252, s78
	v_add3_u32 v253, v193, v253, s78
	v_lshrrev_b32_e32 v252, 16, v252
	v_and_or_b32 v251, v253, s79, v252
	global_store_dwordx4 v254, v[248:251], s[98:99]
	s_xor_b32 s96, s96, 0x4100
	s_add_u32 s76, s76, 311
	s_sub_u32 s77, s77, 1
	s_cmp_lg_u32 s77, 0
	s_cbranch_scc1 .Ltrp0_batch
	s_waitcnt vmcnt(0) lgkmcnt(0)
	s_barrier
	v_readlane_b32 s64, v255, 0
	v_readlane_b32 s65, v255, 1
	v_readlane_b32 s66, v255, 2
	v_readlane_b32 s67, v255, 3
	v_readlane_b32 s68, v255, 4
	v_readlane_b32 s69, v255, 5
	v_readlane_b32 s70, v255, 6
	v_readlane_b32 s71, v255, 7
	v_readlane_b32 s72, v255, 8
	v_readlane_b32 s73, v255, 9
	v_readlane_b32 s74, v255, 10
	v_readlane_b32 s75, v255, 11
	v_readlane_b32 s76, v255, 12
	v_readlane_b32 s77, v255, 13
	v_readlane_b32 s78, v255, 14
	v_readlane_b32 s79, v255, 15
	v_readlane_b32 s80, v255, 16
	v_readlane_b32 s81, v255, 17
	v_readlane_b32 s82, v255, 18
	v_readlane_b32 s83, v255, 19
	v_readlane_b32 s84, v255, 20
	v_readlane_b32 s85, v255, 21
	v_readlane_b32 s86, v255, 22
	v_readlane_b32 s87, v255, 23
	v_readlane_b32 s88, v255, 24
	v_readlane_b32 s89, v255, 25
	v_readlane_b32 s90, v255, 26
	v_readlane_b32 s91, v255, 27
	v_readlane_b32 s92, v255, 28
	v_readlane_b32 s93, v255, 29
	v_readlane_b32 s94, v255, 30
	v_readlane_b32 s95, v255, 31
	v_readlane_b32 s96, v255, 32
	v_readlane_b32 s97, v255, 33
	v_readlane_b32 s98, v255, 34
	v_readlane_b32 s99, v255, 35
	v_readlane_b32 vcc_lo, v255, 36
	v_readlane_b32 vcc_hi, v255, 37
	s_nop 4

; __device__ __forceinline__ TrJob tr_decode(const Params& p, char* ws, int job) {
;   TrJob t;
;   int l = job / TJ_PER_LAYER, rj = job % TJ_PER_LAYER;
;   if (rj < 640) {
;     t.src = p.w_in + (size_t)l * 1024 * 2560; t.K = 1024; t.N = 2560; t.kt = rj / 40; t.nt = rj % 40;
;     t.dst = (u16*)(ws + OFF_WINT) + (size_t)l * 2560 * 1024; t.mode = 0;
;   } else if (rj < 896) {
;     rj -= 640;
;     t.src = p.w_out + (size_t)l * 1024 * 1024; t.K = 1024; t.N = 1024; t.kt = rj / 16; t.nt = rj % 16;
;     t.dst = (u16*)(ws + OFF_WOUTT) + (size_t)l * 1024 * 1024; t.mode = 0;
;   } else {
;     rj -= 896;
;     int e = rj / 1536, q = rj % 1536;
;     size_t eo = (size_t)(l * 16 + e);
;     if (q < 512) {
;       t.src = p.w_gate + eo * 1024 * 2048; t.K = 1024; t.N = 2048; t.kt = q / 32; t.nt = q % 32;
;       t.dst = (u16*)(ws + OFF_WGUT) + eo * 4096 * 1024; t.mode = 1;
;     } else if (q < 1024) {
;       q -= 512;
;       t.src = p.w_up + eo * 1024 * 2048; t.K = 1024; t.N = 2048; t.kt = q / 32; t.nt = q % 32;
;       t.dst = (u16*)(ws + OFF_WGUT) + eo * 4096 * 1024; t.mode = 2;
;     } else {
;       q -= 1024;
;       t.src = p.w_down + eo * 2048 * 1024; t.K = 2048; t.N = 1024; t.kt = q / 16; t.nt = q % 16;
;       t.dst = (u16*)(ws + OFF_WDT) + eo * 1024 * 2048; t.mode = 0;
;     }
;   }
; __device__ __forceinline__ void p0_transposes(const Params& p, char* smem, int bid, int nb, int jlo, int jhi) {
;     ...
;   for (; j < jhi; j += 2 * nb) {
;     const int jn = j + 2 * nb;
;     if (jn < jhi) { tr_load(p, ws, jn, tid, n0); tr_load(p, ws, jn + 1, tid, n1); }
.LBB0_174:
	s_add_i32 s96, s97, s75
	s_cmp_gt_i32 s96, 0x7475
	s_cselect_b64 s[0:1], -1, 0
	s_and_b64 vcc, exec, s[0:1]
	s_cbranch_vccnz .LBB0_208
	s_mul_hi_i32 s10, s96, 0x5254e78f
	s_lshr_b32 s11, s10, 31
	s_ashr_i32 s10, s10, 13
	s_add_i32 s52, s10, s11
	s_mul_i32 s10, s52, 0xffff9c80
	s_add_i32 s10, s96, s10
	s_cmpk_gt_i32 s10, 0x27f
	s_mov_b64 s[58:59], -1
	s_cbranch_scc0 .LBB0_189
	s_cmpk_gt_u32 s10, 0x37f
	s_cbranch_scc0 .LBB0_186
	s_add_i32 s11, s10, 0xfc80
	s_and_b32 s33, s11, 0xffff
	s_mul_i32 s33, s33, 0xaaab
	s_lshr_b32 s33, s33, 26
	s_mul_i32 s40, s33, 0x600
	s_sub_i32 s11, s11, s40
	s_and_b32 s40, s11, 0xffff
	s_lshl_b32 s11, s52, 4
	s_add_i32 s54, s11, s33
	s_ashr_i32 s55, s54, 31
	s_lshl_b64 s[58:59], s[54:55], 23
	s_cmpk_gt_u32 s40, 0x1ff
	s_mov_b64 s[60:61], -1
	s_cbranch_scc0 .LBB0_183
	s_cmpk_gt_u32 s40, 0x3ff
	s_mov_b64 s[56:57], -1
	s_cbranch_scc0 .LBB0_180
	v_readlane_b32 s12, v238, 25
	s_add_i32 s11, s40, 0xfffffc00
	v_readlane_b32 s18, v238, 31
	v_readlane_b32 s19, v238, 32
	s_add_u32 s54, s18, s58
	v_readlane_b32 s13, v238, 26
	v_readlane_b32 s14, v238, 27
	v_readlane_b32 s15, v238, 28
	v_readlane_b32 s16, v238, 29
	v_readlane_b32 s17, v238, 30
	s_addc_u32 s55, s19, s59
	s_lshr_b32 s33, s11, 4
	s_and_b32 s11, s40, 15
	s_mov_b64 s[56:57], 0
